# mem K/V projection re-tiled: 512 sub-tiles of 32x32 (one per half-WG, K split over 4 waves, fragments loaded straight from global, LDS reduction) instead of 32 fetch-bound 128x128 tiles on 16 WGs
# speedup vs baseline: 1.0026x; 1.0026x over previous
; DI unsigned pk2(float a, float b) { f32x2 v = {a, b}; return __builtin_bit_cast(unsigned, __builtin_convertvector(v, bf2_t)); }
; DI bf16_t tobf(float a) { return (bf16_t)(pk2(a, 0.f) & 0xffffu); }
; #define VB ((int)blockIdx.x * 2 + vhalf())
; template <typename T> DI T* opaque(T* p) { asm volatile("" : "+v"(p) : : "memory"); return p; }
; DI void st_rm(const f32x16 (&acc)[2][2], bf16_t* base, int ld, float scale, int r, int h) {
;     bf16_t* pb = base + (size_t)(4 * h) * ld + r;
; #pragma unroll
;     for (int mi = 0; mi < 2; ++mi)
; #pragma unroll
;         for (int qd = 0; qd < 4; ++qd) {
;             bf16_t* q = opaque(pb + (size_t)(32 * mi + 8 * qd) * ld);
; #pragma unroll
;             for (int e = 0; e < 4; ++e)
; #pragma unroll
;                 for (int ni = 0; ni < 2; ++ni) q[(size_t)e * ld + 32 * ni] = tobf(acc[mi][ni][4 * qd + e] * scale);
;         }
; }
; DI void st_tr(const f32x16 (&acc)[2][2], bf16_t* base, int ld, float scale, int r, int h) {
;     bf16_t* pb = base + (size_t)r * ld + 4 * h;
; #pragma unroll
;     for (int ni = 0; ni < 2; ++ni) {
;         bf16_t* q = opaque(pb + (size_t)(32 * ni) * ld);
; #pragma unroll
;         for (int mi = 0; mi < 2; ++mi)
; #pragma unroll
;             for (int qd = 0; qd < 4; ++qd) {
;                 u32x2 v;
;                 v.x = pk2(acc[mi][ni][4 * qd] * scale, acc[mi][ni][4 * qd + 1] * scale);
;                 v.y = pk2(acc[mi][ni][4 * qd + 2] * scale, acc[mi][ni][4 * qd + 3] * scale);
;                 *(u32x2*)(q + 32 * mi + 8 * qd) = v;
;             }
;     }
; }
; DI void phase1(const Params& p, int l, unsigned char* smem) {
;     ...
;         for (int t = VB - 256; t >= 0 && t < 32; t += VG) {
;             const int m0 = (t >> 2) * 128, n0 = (t & 3) * 128;
;             f32x16 acc[2][2]; zero4(acc);
;             gemm_accum(acc, (const bf16_t*)(ws + O_MEMB) + (size_t)m0 * 1024, 1024, (const bf16_t*)(ws + O_WMEM + l * SZ_WMEM) + (size_t)n0 * 1024, 1024, 16, hs);
;             const int row0 = m0 + 64 * wr4, b = row0 >> 8, j0 = row0 & 255, gc = n0 + 64 * wc4;
;             if (gc < 256) st_rm(acc, (bf16_t*)(ws + O_MEMK) + ((size_t)(b * 4 + (gc >> 6)) * 256 + j0) * 64, 64, 1.f, r4, h4);
;             else st_tr(acc, (bf16_t*)(ws + O_MEMVT) + (size_t)(b * 4 + ((gc - 256) >> 6)) * 64 * 256 + j0, 256, 1.f, r4, h4);
;         }
.LBB0_512:
	s_mov_b32 s0, s72
	s_mov_b32 s1, s49
	v_writelane_b32 v254, s0, 54
	v_readfirstlane_b32 s4, v214
	s_lshr_b32 s4, s4, 8
	v_writelane_b32 v254, s1, 55
	s_lshl_b64 s[0:1], s[0:1], 20
	v_writelane_b32 v254, s0, 56
	s_nop 1
	v_writelane_b32 v254, s1, 57
	v_readlane_b32 s0, v253, 39
	s_add_i32 s12, s0, s4
	s_add_u32 s13, s8, 0x19d80000
	s_addc_u32 s14, s9, 0
	v_readlane_b32 s0, v254, 56
	v_readlane_b32 s1, v254, 57
	s_add_u32 s10, s8, s0
	s_addc_u32 s11, s9, s1
	s_add_u32 s15, s10, 0x2080000
	s_addc_u32 s16, s11, 0
	s_add_u32 s6, s8, 0x19f80000
	s_addc_u32 s7, s9, 0
	s_add_u32 s10, s8, 0x1a000000
	s_addc_u32 s11, s9, 0
	s_mul_i32 s17, s4, 0x12400
	s_add_i32 s18, s12, 0x100
	s_and_b32 s18, s18, 0x1ff
	s_lshr_b32 s19, s18, 4
	s_and_b32 s20, s18, 15
	v_and_b32_e32 v0, 31, v215
	v_bfe_u32 v2, v215, 5, 1
	v_lshrrev_b32_e32 v3, 6, v215
	v_lshlrev_b32_e32 v4, 11, v0
	v_lshl_add_u32 v4, v3, 9, v4
	v_lshl_add_u32 v4, v2, 4, v4
	s_lshl_b32 s21, s19, 16
	s_add_u32 s22, s13, s21
	s_addc_u32 s23, s14, 0
	s_lshl_b32 s21, s20, 16
	s_add_u32 s24, s15, s21
	s_addc_u32 s25, s16, 0
	global_load_dwordx4 v[8:11], v4, s[22:23] offset:0
	global_load_dwordx4 v[12:15], v4, s[22:23] offset:32
	global_load_dwordx4 v[16:19], v4, s[22:23] offset:64
	global_load_dwordx4 v[20:23], v4, s[22:23] offset:96
	global_load_dwordx4 v[24:27], v4, s[22:23] offset:128
	global_load_dwordx4 v[28:31], v4, s[22:23] offset:160
	global_load_dwordx4 v[32:35], v4, s[22:23] offset:192
	global_load_dwordx4 v[36:39], v4, s[22:23] offset:224
	global_load_dwordx4 v[40:43], v4, s[22:23] offset:256
	global_load_dwordx4 v[44:47], v4, s[22:23] offset:288
	global_load_dwordx4 v[48:51], v4, s[22:23] offset:320
	global_load_dwordx4 v[52:55], v4, s[22:23] offset:352
	global_load_dwordx4 v[56:59], v4, s[22:23] offset:384
	global_load_dwordx4 v[60:63], v4, s[22:23] offset:416
	global_load_dwordx4 v[64:67], v4, s[22:23] offset:448
	global_load_dwordx4 v[68:71], v4, s[22:23] offset:480
	global_load_dwordx4 v[72:75], v4, s[24:25] offset:0
	global_load_dwordx4 v[76:79], v4, s[24:25] offset:32
	global_load_dwordx4 v[80:83], v4, s[24:25] offset:64
	global_load_dwordx4 v[84:87], v4, s[24:25] offset:96
	global_load_dwordx4 v[88:91], v4, s[24:25] offset:128
	global_load_dwordx4 v[92:95], v4, s[24:25] offset:160
	global_load_dwordx4 v[96:99], v4, s[24:25] offset:192
	global_load_dwordx4 v[100:103], v4, s[24:25] offset:224
	global_load_dwordx4 v[104:107], v4, s[24:25] offset:256
	global_load_dwordx4 v[108:111], v4, s[24:25] offset:288
	global_load_dwordx4 v[112:115], v4, s[24:25] offset:320
	global_load_dwordx4 v[116:119], v4, s[24:25] offset:352
	global_load_dwordx4 v[120:123], v4, s[24:25] offset:384
	global_load_dwordx4 v[124:127], v4, s[24:25] offset:416
	global_load_dwordx4 v[128:131], v4, s[24:25] offset:448
	global_load_dwordx4 v[132:135], v4, s[24:25] offset:480
	v_and_b32_e32 v5, 63, v215
	v_lshlrev_b32_e32 v5, 4, v5
	v_lshl_add_u32 v6, v3, 12, v5
	v_add_u32_e32 v6, s17, v6
	v_lshl_add_u32 v7, v3, 10, v5
	v_add_u32_e32 v7, s17, v7
	s_waitcnt vmcnt(15)
	v_mfma_f32_32x32x16_bf16 v[140:155], v[8:11], v[72:75], 0
	s_waitcnt vmcnt(14)
	v_mfma_f32_32x32x16_bf16 v[140:155], v[12:15], v[76:79], v[140:155]
	s_waitcnt vmcnt(13)
	v_mfma_f32_32x32x16_bf16 v[140:155], v[16:19], v[80:83], v[140:155]
	s_waitcnt vmcnt(12)
	v_mfma_f32_32x32x16_bf16 v[140:155], v[20:23], v[84:87], v[140:155]
	s_waitcnt vmcnt(11)
	v_mfma_f32_32x32x16_bf16 v[140:155], v[24:27], v[88:91], v[140:155]
	s_waitcnt vmcnt(10)
	v_mfma_f32_32x32x16_bf16 v[140:155], v[28:31], v[92:95], v[140:155]
	s_waitcnt vmcnt(9)
	v_mfma_f32_32x32x16_bf16 v[140:155], v[32:35], v[96:99], v[140:155]
	s_waitcnt vmcnt(8)
	v_mfma_f32_32x32x16_bf16 v[140:155], v[36:39], v[100:103], v[140:155]
	s_waitcnt vmcnt(7)
	v_mfma_f32_32x32x16_bf16 v[140:155], v[40:43], v[104:107], v[140:155]
	s_waitcnt vmcnt(6)
	v_mfma_f32_32x32x16_bf16 v[140:155], v[44:47], v[108:111], v[140:155]
	s_waitcnt vmcnt(5)
	v_mfma_f32_32x32x16_bf16 v[140:155], v[48:51], v[112:115], v[140:155]
	s_waitcnt vmcnt(4)
	v_mfma_f32_32x32x16_bf16 v[140:155], v[52:55], v[116:119], v[140:155]
	s_waitcnt vmcnt(3)
	v_mfma_f32_32x32x16_bf16 v[140:155], v[56:59], v[120:123], v[140:155]
	s_waitcnt vmcnt(2)
	v_mfma_f32_32x32x16_bf16 v[140:155], v[60:63], v[124:127], v[140:155]
	s_waitcnt vmcnt(1)
	v_mfma_f32_32x32x16_bf16 v[140:155], v[64:67], v[128:131], v[140:155]
	s_waitcnt vmcnt(0)
	v_mfma_f32_32x32x16_bf16 v[140:155], v[68:71], v[132:135], v[140:155]
	s_barrier
	s_nop 7
	s_nop 3
	ds_write_b128 v6, v[140:143]
	ds_write_b128 v6, v[144:147] offset:1024
	ds_write_b128 v6, v[148:151] offset:2048
	ds_write_b128 v6, v[152:155] offset:3072
	s_waitcnt lgkmcnt(0)
	s_barrier
	ds_read_b128 v[160:163], v7
	ds_read_b128 v[164:167], v7 offset:4096
	ds_read_b128 v[168:171], v7 offset:8192
	ds_read_b128 v[172:175], v7 offset:12288
	s_lshr_b32 s21, s19, 3
	s_lshl_b32 s21, s21, 2
	s_and_b32 s26, s19, 7
	s_lshl_b32 s26, s26, 5
	s_waitcnt lgkmcnt(0)
	v_add_f32_e32 v160, v160, v164
	v_add_f32_e32 v168, v168, v172
	v_add_f32_e32 v161, v161, v165
	v_add_f32_e32 v169, v169, v173
	v_add_f32_e32 v162, v162, v166
	v_add_f32_e32 v170, v170, v174
	v_add_f32_e32 v163, v163, v167
	v_add_f32_e32 v171, v171, v175
	v_add_f32_e32 v160, v160, v168
	v_add_f32_e32 v161, v161, v169
	v_add_f32_e32 v162, v162, v170
	v_add_f32_e32 v163, v163, v171
	v_cvt_pk_bf16_f32 v164, v160, v161
	v_cvt_pk_bf16_f32 v165, v162, v163
	v_lshlrev_b32_e32 v8, 3, v3
	v_lshl_add_u32 v8, v2, 2, v8
	s_cmp_gt_u32 s20, 7
	s_cbranch_scc1 .Lmkv_vpart
	s_lshr_b32 s27, s20, 1
	s_add_i32 s27, s27, s21
	s_lshl_b32 s27, s27, 15
	s_lshl_b32 s0, s26, 7
	s_add_i32 s27, s27, s0
	s_and_b32 s0, s20, 1
	s_lshl_b32 s0, s0, 6
	s_add_i32 s27, s27, s0
	s_add_u32 s6, s6, s27
	s_addc_u32 s7, s7, 0
	v_lshlrev_b32_e32 v9, 7, v8
	v_lshl_add_u32 v9, v0, 1, v9
	global_store_short v9, v164, s[6:7]
	global_store_short_d16_hi v9, v164, s[6:7] offset:128
	global_store_short v9, v165, s[6:7] offset:256
	global_store_short_d16_hi v9, v165, s[6:7] offset:384
	s_branch .LBB0_525
.Lmkv_vpart:
	s_sub_i32 s0, s20, 8
	s_lshr_b32 s27, s0, 1
	s_add_i32 s27, s27, s21
	s_lshl_b32 s27, s27, 15
	s_and_b32 s0, s0, 1
	s_lshl_b32 s0, s0, 14
	s_add_i32 s27, s27, s0
	s_lshl_b32 s0, s26, 1
	s_add_i32 s27, s27, s0
	s_add_u32 s10, s10, s27
	s_addc_u32 s11, s11, 0
	v_lshlrev_b32_e32 v9, 9, v0
	v_lshl_add_u32 v9, v8, 1, v9
	global_store_dwordx2 v9, v[164:165], s[10:11]
	s_branch .LBB0_525
